# v22 + RG-LRU: next task's conv + LDS staging done in the current task's look-back window (renamed temporaries), loop top keeps the scalar bookkeeping
# baseline (speedup 1.0000x reference)
.LBB0_307:
	s_and_b32 s41, s40, 7
	s_cmp_eq_u32 s41, s2
	s_cbranch_scc1 .LBB0_309
	s_lshl_b32 s0, s41, 6
	v_or_b32_e32 v18, s0, v121
	s_mov_b64 s[42:43], s[52:53]
	v_readlane_b32 s52, v254, 60
	v_lshlrev_b32_e32 v38, 2, v18
	v_mov_b32_e32 v39, v196
	v_readlane_b32 s64, v255, 8
	v_readlane_b32 s65, v255, 9
	v_readlane_b32 s53, v254, 61
	v_readlane_b32 s54, v254, 62
	v_readlane_b32 s55, v254, 63
	v_readlane_b32 s56, v255, 0
	v_readlane_b32 s57, v255, 1
	v_readlane_b32 s58, v255, 2
	v_readlane_b32 s59, v255, 3
	v_readlane_b32 s60, v255, 4
	v_readlane_b32 s61, v255, 5
	v_readlane_b32 s62, v255, 6
	v_readlane_b32 s63, v255, 7
	v_readlane_b32 s66, v255, 10
	v_readlane_b32 s67, v255, 11
	v_lshl_add_u64 v[50:51], s[64:65], 0, v[38:39]
	s_mov_b64 s[16:17], 0x1000
	s_movk_i32 s1, 0x1000
	s_nop 1
	global_load_dwordx4 v[22:25], v38, s[66:67] offset:16
	global_load_dwordx4 v[18:21], v38, s[64:65] offset:16
	global_load_dwordx4 v[30:33], v38, s[66:67]
	global_load_dwordx4 v[26:29], v38, s[64:65]
	global_load_dwordx4 v[34:37], v38, s[64:65] offset:2064
	s_nop 0
	global_load_dwordx4 v[38:41], v38, s[64:65] offset:2048
	v_lshl_add_u64 v[42:43], v[50:51], 0, s[16:17]
	v_add_co_u32_e32 v52, vcc, s1, v50
	s_mov_b64 s[16:17], 0x1800
	v_or_b32_e32 v58, s0, v120
	v_readlane_b32 s52, v255, 12
	v_readlane_b32 s0, v255, 43
	v_addc_co_u32_e32 v53, vcc, 0, v51, vcc
	v_lshl_add_u64 v[50:51], v[50:51], 0, s[16:17]
	v_lshlrev_b32_e32 v58, 2, v58
	v_readlane_b32 s54, v255, 14
	v_readlane_b32 s55, v255, 15
	v_readlane_b32 s1, v255, 44
	global_load_dwordx4 v[46:49], v[52:53], off
	s_nop 0
	global_load_dwordx4 v[42:45], v[42:43], off offset:16
	s_nop 0
	global_load_dwordx4 v[54:57], v[52:53], off offset:2048
	s_nop 0
	global_load_dwordx4 v[50:53], v[50:51], off offset:16
	v_readlane_b32 s58, v255, 18
	v_readlane_b32 s59, v255, 19
	global_load_dword v153, v58, s[54:55]
	s_nop 3
	global_load_dword v154, v58, s[58:59]
	global_load_dword v155, v58, s[0:1]
	s_lshl_b32 s0, s41, 13
	s_mov_b32 s1, s46
	v_lshl_add_u64 v[74:75], v[96:97], 0, s[0:1]
	global_load_dwordx4 v[70:73], v[74:75], off
	global_load_dwordx4 v[66:69], v[74:75], off offset:64
	global_load_dwordx4 v[62:65], v[74:75], off offset:2048
	global_load_dwordx4 v[58:61], v[74:75], off offset:2112
	v_add_co_u32_e32 v74, vcc, 0x1000, v74
	v_readlane_b32 s60, v255, 20
	s_nop 0
	v_addc_co_u32_e32 v75, vcc, 0, v75, vcc
	global_load_dwordx4 v[86:89], v[74:75], off
	global_load_dwordx4 v[82:85], v[74:75], off offset:64
	global_load_dwordx4 v[78:81], v[74:75], off offset:2048
	s_nop 0
	global_load_dwordx4 v[74:77], v[74:75], off offset:2112
	v_readlane_b32 s61, v255, 21
	v_readlane_b32 s62, v255, 22
	v_readlane_b32 s63, v255, 23
	v_readlane_b32 s53, v255, 13
	v_readlane_b32 s62, v255, 51
	v_readlane_b32 s60, v255, 49
	s_mov_b64 s[52:53], s[42:43]
	v_readlane_b32 s63, v255, 52
	v_readlane_b32 s61, v255, 50
	s_mov_b32 s2, s41
	v_readlane_b32 s56, v255, 16
	v_readlane_b32 s57, v255, 17
	v_readlane_b32 s64, v255, 24
	v_readlane_b32 s65, v255, 25
	v_readlane_b32 s66, v255, 26
	v_readlane_b32 s67, v255, 27
	s_waitcnt vmcnt(0)
	s_barrier
	v_lshlrev_b32_e32 v98, 16, v6
	v_and_b32_e32 v99, 0xffff0000, v6
	v_pk_fma_f32 v[98:99], v[26:27], v[98:99], v[30:31]
	v_lshlrev_b32_e32 v100, 16, v2
	v_and_b32_e32 v101, 0xffff0000, v2
	v_pk_fma_f32 v[98:99], v[38:39], v[100:101], v[98:99]
	v_lshlrev_b32_e32 v100, 16, v10
	v_and_b32_e32 v101, 0xffff0000, v10
	v_pk_fma_f32 v[98:99], v[46:47], v[100:101], v[98:99]
	v_lshlrev_b32_e32 v100, 16, v14
	v_and_b32_e32 v101, 0xffff0000, v14
	v_pk_fma_f32 v[98:99], v[54:55], v[100:101], v[98:99]
	v_lshlrev_b32_e32 v100, 16, v7
	v_and_b32_e32 v101, 0xffff0000, v7
	v_pk_fma_f32 v[100:101], v[28:29], v[100:101], v[32:33]
	v_lshlrev_b32_e32 v102, 16, v3
	v_and_b32_e32 v103, 0xffff0000, v3
	v_pk_fma_f32 v[100:101], v[40:41], v[102:103], v[100:101]
	v_lshlrev_b32_e32 v102, 16, v11
	v_and_b32_e32 v103, 0xffff0000, v11
	v_pk_fma_f32 v[100:101], v[48:49], v[102:103], v[100:101]
	v_lshlrev_b32_e32 v102, 16, v15
	v_and_b32_e32 v103, 0xffff0000, v15
	v_pk_fma_f32 v[100:101], v[56:57], v[102:103], v[100:101]
	v_lshlrev_b32_e32 v102, 16, v8
	v_and_b32_e32 v103, 0xffff0000, v8
	v_pk_fma_f32 v[102:103], v[18:19], v[102:103], v[22:23]
	v_lshlrev_b32_e32 v104, 16, v4
	v_and_b32_e32 v105, 0xffff0000, v4
	v_pk_fma_f32 v[102:103], v[34:35], v[104:105], v[102:103]
	v_lshlrev_b32_e32 v104, 16, v12
	v_and_b32_e32 v105, 0xffff0000, v12
	v_pk_fma_f32 v[102:103], v[42:43], v[104:105], v[102:103]
	v_lshlrev_b32_e32 v104, 16, v16
	v_and_b32_e32 v105, 0xffff0000, v16
	v_pk_fma_f32 v[102:103], v[50:51], v[104:105], v[102:103]
	v_lshlrev_b32_e32 v104, 16, v9
	v_and_b32_e32 v105, 0xffff0000, v9
	v_pk_fma_f32 v[104:105], v[20:21], v[104:105], v[24:25]
	v_lshlrev_b32_e32 v106, 16, v5
	v_and_b32_e32 v107, 0xffff0000, v5
	v_pk_fma_f32 v[104:105], v[36:37], v[106:107], v[104:105]
	v_lshlrev_b32_e32 v106, 16, v13
	v_and_b32_e32 v107, 0xffff0000, v13
	v_pk_fma_f32 v[104:105], v[44:45], v[106:107], v[104:105]
	v_lshlrev_b32_e32 v106, 16, v17
	v_and_b32_e32 v107, 0xffff0000, v17
	v_pk_fma_f32 v[104:105], v[52:53], v[106:107], v[104:105]
	v_cvt_pk_bf16_f32 v106, v98, v99
	v_cvt_pk_bf16_f32 v107, v100, v101
	v_cvt_pk_bf16_f32 v108, v102, v103
	v_add_u32_e32 v110, v122, v90
	v_cvt_pk_bf16_f32 v109, v104, v105
	ds_write_b128 v110, v[106:109]
	ds_write_b128 v123, v[98:101] offset:9216
	ds_write_b128 v123, v[102:105] offset:9232
.LBB0_309:
	s_load_dword s15, s[78:79], 0x0
	s_waitcnt lgkmcnt(0)
	s_add_i32 s15, s15, s40
	s_cmpk_gt_i32 s15, 0x7ff
	s_cselect_b64 s[16:17], -1, 0
	s_and_b64 vcc, exec, s[16:17]
	s_cbranch_vccnz .LBB0_319
	s_lshl_b32 s0, s15, 8
	s_and_b32 s42, s15, 0xffffffc0
	s_and_b32 s33, s0, 0x3800
	s_lshl_b32 s0, s15, 7
	v_add_u32_e32 v14, s42, v124
	s_and_b32 s0, s0, 0x380
	s_mov_b32 s1, s46
	v_mov_b32_e32 v2, v196
	v_mov_b32_e32 v3, v196
	v_lshl_add_u64 v[98:99], v[92:93], 0, s[0:1]
	v_cmp_lt_i32_e32 vcc, -1, v14
	v_mov_b64_e32 v[6:7], v[2:3]
	v_mov_b64_e32 v[8:9], v[2:3]
	s_and_saveexec_b64 s[0:1], vcc
	s_cbranch_execz .LBB0_312
	v_add_u32_e32 v4, s33, v14
	s_movk_i32 s43, 0xc00
	v_mad_u64_u32 v[4:5], s[44:45], v4, s43, v[98:99]
	global_load_dwordx4 v[6:9], v[4:5], off

.LBB0_331:
	v_fmac_f32_e32 v115, v114, v117
	v_mul_f32_e32 v177, v114, v178
	s_and_saveexec_b64 s[0:1], s[52:53]
	s_cbranch_execz .LBB0_340
	s_add_i32 s68, s73, s33
	s_ashr_i32 s69, s68, 31
	s_lshl_b64 s[68:69], s[68:69], 12
	s_add_u32 s68, s36, s68
	v_or_b32_e32 v114, 1, v177
	s_addc_u32 s69, s37, s69
	global_store_dwordx2 v112, v[114:115], s[68:69] sc1
	s_or_b64 exec, exec, s[0:1]
	s_waitcnt vmcnt(1)
	v_lshlrev_b32_e32 v179, 16, v101
	v_mul_f32_e32 v222, 0x3d372713, v179
	v_mul_f32_e32 v222, v222, v179
	v_fma_f32 v222, v222, v179, v179
	v_mul_f32_e32 v222, 0x3f4c422a, v222
	v_add_f32_e32 v222, v222, v222
	v_mul_f32_e32 v222, 0x3fb8aa3b, v222
	v_exp_f32_e32 v222, v222
	v_mul_f32_e32 v179, 0.5, v179
	v_add_f32_e32 v222, 1.0, v222
	v_rcp_f32_e32 v222, v222
	s_nop 0
	v_fma_f32 v222, v222, -2.0, 1.0
	v_add_f32_e32 v222, 1.0, v222
	v_mul_f32_e32 v188, v179, v222
	v_lshlrev_b32_e32 v179, 16, v162
	v_mul_f32_e32 v222, 0x3d372713, v179
	v_mul_f32_e32 v222, v222, v179
	v_fma_f32 v222, v222, v179, v179
	v_mul_f32_e32 v222, 0x3f4c422a, v222
	v_add_f32_e32 v222, v222, v222
	v_mul_f32_e32 v222, 0x3fb8aa3b, v222
	v_exp_f32_e32 v222, v222
	v_mul_f32_e32 v179, 0.5, v179
	v_add_f32_e32 v222, 1.0, v222
	v_rcp_f32_e32 v222, v222
	s_nop 0
	v_fma_f32 v222, v222, -2.0, 1.0
	v_add_f32_e32 v222, 1.0, v222
	v_mul_f32_e32 v189, v179, v222
	v_lshlrev_b32_e32 v179, 16, v161
	v_mul_f32_e32 v222, 0x3d372713, v179
	v_mul_f32_e32 v222, v222, v179
	v_fma_f32 v222, v222, v179, v179
	v_mul_f32_e32 v222, 0x3f4c422a, v222
	v_add_f32_e32 v222, v222, v222
	v_mul_f32_e32 v222, 0x3fb8aa3b, v222
	v_exp_f32_e32 v222, v222
	v_mul_f32_e32 v179, 0.5, v179
	v_add_f32_e32 v222, 1.0, v222
	v_rcp_f32_e32 v222, v222
	s_nop 0
	v_fma_f32 v222, v222, -2.0, 1.0
	v_add_f32_e32 v222, 1.0, v222
	v_mul_f32_e32 v190, v179, v222
	v_lshlrev_b32_e32 v179, 16, v160
	v_mul_f32_e32 v222, 0x3d372713, v179
	v_mul_f32_e32 v222, v222, v179
	v_fma_f32 v222, v222, v179, v179
	v_mul_f32_e32 v222, 0x3f4c422a, v222
	v_add_f32_e32 v222, v222, v222
	v_mul_f32_e32 v222, 0x3fb8aa3b, v222
	v_exp_f32_e32 v222, v222
	v_mul_f32_e32 v179, 0.5, v179
	v_add_f32_e32 v222, 1.0, v222
	v_rcp_f32_e32 v222, v222
	s_nop 0
	v_fma_f32 v222, v222, -2.0, 1.0
	v_add_f32_e32 v222, 1.0, v222
	v_mul_f32_e32 v191, v179, v222
	v_lshlrev_b32_e32 v179, 16, v159
	v_mul_f32_e32 v222, 0x3d372713, v179
	v_mul_f32_e32 v222, v222, v179
	v_fma_f32 v222, v222, v179, v179
	v_mul_f32_e32 v222, 0x3f4c422a, v222
	v_add_f32_e32 v222, v222, v222
	v_mul_f32_e32 v222, 0x3fb8aa3b, v222
	v_exp_f32_e32 v222, v222
	v_mul_f32_e32 v179, 0.5, v179
	v_add_f32_e32 v222, 1.0, v222
	v_rcp_f32_e32 v222, v222
	s_nop 0
	v_fma_f32 v222, v222, -2.0, 1.0
	v_add_f32_e32 v222, 1.0, v222
	v_mul_f32_e32 v192, v179, v222
	v_lshlrev_b32_e32 v179, 16, v158
	v_mul_f32_e32 v222, 0x3d372713, v179
	v_mul_f32_e32 v222, v222, v179
	v_fma_f32 v222, v222, v179, v179
	v_mul_f32_e32 v222, 0x3f4c422a, v222
	v_add_f32_e32 v222, v222, v222
	v_mul_f32_e32 v222, 0x3fb8aa3b, v222
	v_exp_f32_e32 v222, v222
	v_mul_f32_e32 v179, 0.5, v179
	v_add_f32_e32 v222, 1.0, v222
	v_rcp_f32_e32 v222, v222
	s_nop 0
	v_fma_f32 v222, v222, -2.0, 1.0
	v_add_f32_e32 v222, 1.0, v222
	v_mul_f32_e32 v193, v179, v222
	v_lshlrev_b32_e32 v179, 16, v157
	v_mul_f32_e32 v222, 0x3d372713, v179
	v_mul_f32_e32 v222, v222, v179
	v_fma_f32 v222, v222, v179, v179
	v_mul_f32_e32 v222, 0x3f4c422a, v222
	v_add_f32_e32 v222, v222, v222
	v_mul_f32_e32 v222, 0x3fb8aa3b, v222
	v_exp_f32_e32 v222, v222
	v_mul_f32_e32 v179, 0.5, v179
	v_add_f32_e32 v222, 1.0, v222
	v_rcp_f32_e32 v222, v222
	s_nop 0
	v_fma_f32 v222, v222, -2.0, 1.0
	v_add_f32_e32 v222, 1.0, v222
	v_mul_f32_e32 v194, v179, v222
	v_lshlrev_b32_e32 v179, 16, v156
	v_mul_f32_e32 v222, 0x3d372713, v179
	v_mul_f32_e32 v222, v222, v179
	v_fma_f32 v222, v222, v179, v179
	v_mul_f32_e32 v222, 0x3f4c422a, v222
	v_add_f32_e32 v222, v222, v222
	v_mul_f32_e32 v222, 0x3fb8aa3b, v222
	v_exp_f32_e32 v222, v222
	v_mul_f32_e32 v179, 0.5, v179
	v_add_f32_e32 v222, 1.0, v222
	v_rcp_f32_e32 v222, v222
	s_nop 0
	v_fma_f32 v222, v222, -2.0, 1.0
	v_add_f32_e32 v222, 1.0, v222
	v_mul_f32_e32 v195, v179, v222
	s_cmp_lg_u64 s[16:17], 0
	s_cbranch_scc1 .Lrn_nc1
	v_lshlrev_b32_e32 v240, 16, v6
	v_and_b32_e32 v241, 0xffff0000, v6
	v_pk_fma_f32 v[240:241], v[26:27], v[240:241], v[30:31]
	v_lshlrev_b32_e32 v242, 16, v2
	v_and_b32_e32 v243, 0xffff0000, v2
	v_pk_fma_f32 v[240:241], v[38:39], v[242:243], v[240:241]
	v_lshlrev_b32_e32 v242, 16, v10
	v_and_b32_e32 v243, 0xffff0000, v10
	v_pk_fma_f32 v[240:241], v[46:47], v[242:243], v[240:241]
	v_lshlrev_b32_e32 v242, 16, v14
	v_and_b32_e32 v243, 0xffff0000, v14
	v_pk_fma_f32 v[240:241], v[54:55], v[242:243], v[240:241]
	v_lshlrev_b32_e32 v242, 16, v7
	v_and_b32_e32 v243, 0xffff0000, v7
	v_pk_fma_f32 v[242:243], v[28:29], v[242:243], v[32:33]
	v_lshlrev_b32_e32 v244, 16, v3
	v_and_b32_e32 v245, 0xffff0000, v3
	v_pk_fma_f32 v[242:243], v[40:41], v[244:245], v[242:243]
	v_lshlrev_b32_e32 v244, 16, v11
	v_and_b32_e32 v245, 0xffff0000, v11
	v_pk_fma_f32 v[242:243], v[48:49], v[244:245], v[242:243]
	v_lshlrev_b32_e32 v244, 16, v15
	v_and_b32_e32 v245, 0xffff0000, v15
	v_pk_fma_f32 v[242:243], v[56:57], v[244:245], v[242:243]
	v_lshlrev_b32_e32 v244, 16, v8
	v_and_b32_e32 v245, 0xffff0000, v8
	v_pk_fma_f32 v[244:245], v[18:19], v[244:245], v[22:23]
	v_lshlrev_b32_e32 v246, 16, v4
	v_and_b32_e32 v247, 0xffff0000, v4
	v_pk_fma_f32 v[244:245], v[34:35], v[246:247], v[244:245]
	v_lshlrev_b32_e32 v246, 16, v12
	v_and_b32_e32 v247, 0xffff0000, v12
	v_pk_fma_f32 v[244:245], v[42:43], v[246:247], v[244:245]
	v_lshlrev_b32_e32 v246, 16, v16
	v_and_b32_e32 v247, 0xffff0000, v16
	v_pk_fma_f32 v[244:245], v[50:51], v[246:247], v[244:245]
	v_lshlrev_b32_e32 v246, 16, v9
	v_and_b32_e32 v247, 0xffff0000, v9
	v_pk_fma_f32 v[246:247], v[20:21], v[246:247], v[24:25]
	v_lshlrev_b32_e32 v226, 16, v5
	v_and_b32_e32 v227, 0xffff0000, v5
	v_pk_fma_f32 v[246:247], v[36:37], v[226:227], v[246:247]
	v_lshlrev_b32_e32 v226, 16, v13
	v_and_b32_e32 v227, 0xffff0000, v13
	v_pk_fma_f32 v[246:247], v[44:45], v[226:227], v[246:247]
	v_lshlrev_b32_e32 v226, 16, v17
	v_and_b32_e32 v227, 0xffff0000, v17
	v_pk_fma_f32 v[246:247], v[52:53], v[226:227], v[246:247]
	v_cvt_pk_bf16_f32 v226, v240, v241
	v_cvt_pk_bf16_f32 v227, v242, v243
	v_cvt_pk_bf16_f32 v228, v244, v245
	v_add_u32_e32 v232, v122, v90
	v_cvt_pk_bf16_f32 v229, v246, v247
	ds_write_b128 v232, v[226:229]
	ds_write_b128 v123, v[240:243] offset:9216
	ds_write_b128 v123, v[244:247] offset:9232
.Lrn_nc1:
	s_and_saveexec_b64 s[68:69], s[44:45]
	s_cbranch_execnz .LBB0_341

.LBB0_340:
	s_or_b64 exec, exec, s[0:1]
	s_waitcnt vmcnt(0)
	v_lshlrev_b32_e32 v179, 16, v101
	v_mul_f32_e32 v222, 0x3d372713, v179
	v_mul_f32_e32 v222, v222, v179
	v_fma_f32 v222, v222, v179, v179
	v_mul_f32_e32 v222, 0x3f4c422a, v222
	v_add_f32_e32 v222, v222, v222
	v_mul_f32_e32 v222, 0x3fb8aa3b, v222
	v_exp_f32_e32 v222, v222
	v_mul_f32_e32 v179, 0.5, v179
	v_add_f32_e32 v222, 1.0, v222
	v_rcp_f32_e32 v222, v222
	s_nop 0
	v_fma_f32 v222, v222, -2.0, 1.0
	v_add_f32_e32 v222, 1.0, v222
	v_mul_f32_e32 v188, v179, v222
	v_lshlrev_b32_e32 v179, 16, v162
	v_mul_f32_e32 v222, 0x3d372713, v179
	v_mul_f32_e32 v222, v222, v179
	v_fma_f32 v222, v222, v179, v179
	v_mul_f32_e32 v222, 0x3f4c422a, v222
	v_add_f32_e32 v222, v222, v222
	v_mul_f32_e32 v222, 0x3fb8aa3b, v222
	v_exp_f32_e32 v222, v222
	v_mul_f32_e32 v179, 0.5, v179
	v_add_f32_e32 v222, 1.0, v222
	v_rcp_f32_e32 v222, v222
	s_nop 0
	v_fma_f32 v222, v222, -2.0, 1.0
	v_add_f32_e32 v222, 1.0, v222
	v_mul_f32_e32 v189, v179, v222
	v_lshlrev_b32_e32 v179, 16, v161
	v_mul_f32_e32 v222, 0x3d372713, v179
	v_mul_f32_e32 v222, v222, v179
	v_fma_f32 v222, v222, v179, v179
	v_mul_f32_e32 v222, 0x3f4c422a, v222
	v_add_f32_e32 v222, v222, v222
	v_mul_f32_e32 v222, 0x3fb8aa3b, v222
	v_exp_f32_e32 v222, v222
	v_mul_f32_e32 v179, 0.5, v179
	v_add_f32_e32 v222, 1.0, v222
	v_rcp_f32_e32 v222, v222
	s_nop 0
	v_fma_f32 v222, v222, -2.0, 1.0
	v_add_f32_e32 v222, 1.0, v222
	v_mul_f32_e32 v190, v179, v222
	v_lshlrev_b32_e32 v179, 16, v160
	v_mul_f32_e32 v222, 0x3d372713, v179
	v_mul_f32_e32 v222, v222, v179
	v_fma_f32 v222, v222, v179, v179
	v_mul_f32_e32 v222, 0x3f4c422a, v222
	v_add_f32_e32 v222, v222, v222
	v_mul_f32_e32 v222, 0x3fb8aa3b, v222
	v_exp_f32_e32 v222, v222
	v_mul_f32_e32 v179, 0.5, v179
	v_add_f32_e32 v222, 1.0, v222
	v_rcp_f32_e32 v222, v222
	s_nop 0
	v_fma_f32 v222, v222, -2.0, 1.0
	v_add_f32_e32 v222, 1.0, v222
	v_mul_f32_e32 v191, v179, v222
	v_lshlrev_b32_e32 v179, 16, v159
	v_mul_f32_e32 v222, 0x3d372713, v179
	v_mul_f32_e32 v222, v222, v179
	v_fma_f32 v222, v222, v179, v179
	v_mul_f32_e32 v222, 0x3f4c422a, v222
	v_add_f32_e32 v222, v222, v222
	v_mul_f32_e32 v222, 0x3fb8aa3b, v222
	v_exp_f32_e32 v222, v222
	v_mul_f32_e32 v179, 0.5, v179
	v_add_f32_e32 v222, 1.0, v222
	v_rcp_f32_e32 v222, v222
	s_nop 0
	v_fma_f32 v222, v222, -2.0, 1.0
	v_add_f32_e32 v222, 1.0, v222
	v_mul_f32_e32 v192, v179, v222
	v_lshlrev_b32_e32 v179, 16, v158
	v_mul_f32_e32 v222, 0x3d372713, v179
	v_mul_f32_e32 v222, v222, v179
	v_fma_f32 v222, v222, v179, v179
	v_mul_f32_e32 v222, 0x3f4c422a, v222
	v_add_f32_e32 v222, v222, v222
	v_mul_f32_e32 v222, 0x3fb8aa3b, v222
	v_exp_f32_e32 v222, v222
	v_mul_f32_e32 v179, 0.5, v179
	v_add_f32_e32 v222, 1.0, v222
	v_rcp_f32_e32 v222, v222
	s_nop 0
	v_fma_f32 v222, v222, -2.0, 1.0
	v_add_f32_e32 v222, 1.0, v222
	v_mul_f32_e32 v193, v179, v222
	v_lshlrev_b32_e32 v179, 16, v157
	v_mul_f32_e32 v222, 0x3d372713, v179
	v_mul_f32_e32 v222, v222, v179
	v_fma_f32 v222, v222, v179, v179
	v_mul_f32_e32 v222, 0x3f4c422a, v222
	v_add_f32_e32 v222, v222, v222
	v_mul_f32_e32 v222, 0x3fb8aa3b, v222
	v_exp_f32_e32 v222, v222
	v_mul_f32_e32 v179, 0.5, v179
	v_add_f32_e32 v222, 1.0, v222
	v_rcp_f32_e32 v222, v222
	s_nop 0
	v_fma_f32 v222, v222, -2.0, 1.0
	v_add_f32_e32 v222, 1.0, v222
	v_mul_f32_e32 v194, v179, v222
	v_lshlrev_b32_e32 v179, 16, v156
	v_mul_f32_e32 v222, 0x3d372713, v179
	v_mul_f32_e32 v222, v222, v179
	v_fma_f32 v222, v222, v179, v179
	v_mul_f32_e32 v222, 0x3f4c422a, v222
	v_add_f32_e32 v222, v222, v222
	v_mul_f32_e32 v222, 0x3fb8aa3b, v222
	v_exp_f32_e32 v222, v222
	v_mul_f32_e32 v179, 0.5, v179
	v_add_f32_e32 v222, 1.0, v222
	v_rcp_f32_e32 v222, v222
	s_nop 0
	v_fma_f32 v222, v222, -2.0, 1.0
	v_add_f32_e32 v222, 1.0, v222
	v_mul_f32_e32 v195, v179, v222
	s_cmp_lg_u64 s[16:17], 0
	s_cbranch_scc1 .Lrn_nc0
	v_lshlrev_b32_e32 v240, 16, v6
	v_and_b32_e32 v241, 0xffff0000, v6
	v_pk_fma_f32 v[240:241], v[26:27], v[240:241], v[30:31]
	v_lshlrev_b32_e32 v242, 16, v2
	v_and_b32_e32 v243, 0xffff0000, v2
	v_pk_fma_f32 v[240:241], v[38:39], v[242:243], v[240:241]
	v_lshlrev_b32_e32 v242, 16, v10
	v_and_b32_e32 v243, 0xffff0000, v10
	v_pk_fma_f32 v[240:241], v[46:47], v[242:243], v[240:241]
	v_lshlrev_b32_e32 v242, 16, v14
	v_and_b32_e32 v243, 0xffff0000, v14
	v_pk_fma_f32 v[240:241], v[54:55], v[242:243], v[240:241]
	v_lshlrev_b32_e32 v242, 16, v7
	v_and_b32_e32 v243, 0xffff0000, v7
	v_pk_fma_f32 v[242:243], v[28:29], v[242:243], v[32:33]
	v_lshlrev_b32_e32 v244, 16, v3
	v_and_b32_e32 v245, 0xffff0000, v3
	v_pk_fma_f32 v[242:243], v[40:41], v[244:245], v[242:243]
	v_lshlrev_b32_e32 v244, 16, v11
	v_and_b32_e32 v245, 0xffff0000, v11
	v_pk_fma_f32 v[242:243], v[48:49], v[244:245], v[242:243]
	v_lshlrev_b32_e32 v244, 16, v15
	v_and_b32_e32 v245, 0xffff0000, v15
	v_pk_fma_f32 v[242:243], v[56:57], v[244:245], v[242:243]
	v_lshlrev_b32_e32 v244, 16, v8
	v_and_b32_e32 v245, 0xffff0000, v8
	v_pk_fma_f32 v[244:245], v[18:19], v[244:245], v[22:23]
	v_lshlrev_b32_e32 v246, 16, v4
	v_and_b32_e32 v247, 0xffff0000, v4
	v_pk_fma_f32 v[244:245], v[34:35], v[246:247], v[244:245]
	v_lshlrev_b32_e32 v246, 16, v12
	v_and_b32_e32 v247, 0xffff0000, v12
	v_pk_fma_f32 v[244:245], v[42:43], v[246:247], v[244:245]
	v_lshlrev_b32_e32 v246, 16, v16
	v_and_b32_e32 v247, 0xffff0000, v16
	v_pk_fma_f32 v[244:245], v[50:51], v[246:247], v[244:245]
	v_lshlrev_b32_e32 v246, 16, v9
	v_and_b32_e32 v247, 0xffff0000, v9
	v_pk_fma_f32 v[246:247], v[20:21], v[246:247], v[24:25]
	v_lshlrev_b32_e32 v226, 16, v5
	v_and_b32_e32 v227, 0xffff0000, v5
	v_pk_fma_f32 v[246:247], v[36:37], v[226:227], v[246:247]
	v_lshlrev_b32_e32 v226, 16, v13
	v_and_b32_e32 v227, 0xffff0000, v13
	v_pk_fma_f32 v[246:247], v[44:45], v[226:227], v[246:247]
	v_lshlrev_b32_e32 v226, 16, v17
	v_and_b32_e32 v227, 0xffff0000, v17
	v_pk_fma_f32 v[246:247], v[52:53], v[226:227], v[246:247]
	v_cvt_pk_bf16_f32 v226, v240, v241
	v_cvt_pk_bf16_f32 v227, v242, v243
	v_cvt_pk_bf16_f32 v228, v244, v245
	v_add_u32_e32 v232, v122, v90
	v_cvt_pk_bf16_f32 v229, v246, v247
	ds_write_b128 v232, v[226:229]
	ds_write_b128 v123, v[240:243] offset:9216
	ds_write_b128 v123, v[244:247] offset:9232
.Lrn_nc0:
	s_and_saveexec_b64 s[68:69], s[44:45]
	s_cbranch_execz .LBB0_333
